# E-GEMM workgroups: scan decay factor loaded ahead of the K loop; attention staging no longer drains the scan's stores first
# baseline (speedup 1.0000x reference)
; #define PG8_STAGE(bufoff, gbase, voff) do { _Pragma("unroll") for (int _i = 0; _i < 2; ++_i) \
;         __builtin_amdgcn_global_load_lds((const unsigned*)((const char*)(gbase) + (voff)[_i]), (LAS unsigned*)(lds + (bufoff) + ldsw + _i * 8192), 16, 0, 0); } while (0)
; #define PG8_WAIT_V(n) asm volatile("s_waitcnt vmcnt(" #n ")" ::: "memory")
; #define PG8_BAR __builtin_amdgcn_s_barrier()
; template <class Epi, bool ALIGN_EPI>
; __device__ __forceinline__ void gemm_phase(LAS unsigned char* lds, const Gemm g, const Order& S, const Epi& E, const int wave_id) {
;     ...
;     const char* cA = (const char*)g.A + (size_t)cur.z * g.sAz + (size_t)cur.pm * 2 * hstepA + (size_t)cur.k0 * 2; const char* cB = (const char*)g.Bt + (size_t)cur.z * g.sBz + (size_t)cur.pn * 2 * hstepB + (size_t)cur.k0 * 2;
;     PG8_STAGE(PG8_SB(0, 0), cB, voffB); PG8_STAGE(PG8_SB(0, 1), cB + hstepB, voffB); PG8_STAGE(PG8_SA(0, 0), cA, voffA); PG8_STAGE(PG8_SA(0, 1), cA + hstepA, voffA);
;     if (wr == 1) PG8_BAR;
;     PG8_WAIT_V(2); PG8_BAR;
;     PG8_STAGE(PG8_SB(1, 0), cB + kstep, voffB); PG8_STAGE(PG8_SA(1, 0), cA + kstep, voffA); PG8_STAGE(PG8_SB(1, 1), cB + hstepB + kstep, voffB);
;     PG8_WAIT_V(6); PG8_BAR;
;     __device__ __forceinline__ void fused(const Acc& acc, const Unit& u, int wr, int wc, int fr, int fq, LAS unsigned char* lds, int wid, int lane) const {
;     ...
;             const float ar = apow[((g * 17 + 16) * 64 + p) * 2], aim = apow[((g * 17 + 16) * 64 + p) * 2 + 1];
.LBB0_917:
	v_lshl_add_u64 v[2:3], s[2:3], 0, v[160:161]
	v_mov_b32_e32 v67, v161
	v_lshl_add_u64 v[4:5], s[2:3], 0, v[66:67]
	v_mov_b32_e32 v71, v161
	s_add_i32 m0, s22, 0x18000
	v_lshl_add_u64 v[2:3], v[2:3], 0, s[82:83]
	v_lshl_add_u64 v[6:7], s[0:1], 0, v[70:71]
	v_mov_b32_e32 v69, v161
	s_and_b32 s28, s19, 3
	s_waitcnt vmcnt(2)
	s_barrier
	global_load_lds_dwordx4 v[2:3], off
	v_lshl_add_u64 v[2:3], v[4:5], 0, s[82:83]
	s_add_i32 m0, s22, 0x1a000
	s_add_i32 s29, s22, 0x8000
	s_add_i32 s30, s22, 0xa000
	v_lshl_add_u64 v[8:9], s[0:1], 0, v[68:69]
	global_load_lds_dwordx4 v[2:3], off
	v_lshl_add_u64 v[2:3], v[6:7], 0, s[82:83]
	s_mov_b32 m0, s29
	s_add_u32 s4, s2, 0x10080
	global_load_lds_dwordx4 v[2:3], off
	v_lshl_add_u64 v[2:3], v[8:9], 0, s[82:83]
	s_mov_b32 m0, s30
	s_addc_u32 s5, s3, 0
	s_add_i32 s31, s22, 0x1c000
	global_load_lds_dwordx4 v[2:3], off
	v_lshl_add_u64 v[2:3], s[4:5], 0, v[160:161]
	s_mov_b32 m0, s31
	s_add_i32 s34, s22, 0x1e000
	global_load_lds_dwordx4 v[2:3], off
	v_lshl_add_u64 v[2:3], s[4:5], 0, v[66:67]
	s_mov_b32 m0, s34
	v_and_b32_e32 v65, 15, v64
	global_load_lds_dwordx4 v[2:3], off
	v_and_b32_e32 v1, 48, v64
	v_and_b32_e32 v0, 0xfffffc00, v0
	v_lshlrev_b32_e32 v3, 2, v64
	v_lshl_or_b32 v1, v65, 6, v1
	v_lshl_add_u32 v2, s20, 13, v0
	v_and_b32_e32 v3, 32, v3
	v_lshl_add_u32 v0, s28, 12, v0
	s_waitcnt vmcnt(6)
	v_bitop3_b32 v2, v1, v2, v3 bitop3:0xde
	v_bitop3_b32 v72, v1, v0, v3 bitop3:0xde
	v_mov_b32_e32 v0, 0
	s_mov_b32 s35, 0
	s_mov_b64 s[4:5], -1
	s_mov_b64 s[6:7], 0
	v_add_u32_e32 v73, 0, v2
	v_mov_b32_e32 v1, v0
	v_mov_b32_e32 v2, v0
	v_mov_b32_e32 v3, v0
	v_mov_b32_e32 v4, v0
	v_mov_b32_e32 v5, v0
	v_mov_b32_e32 v6, v0
	v_mov_b32_e32 v7, v0
	v_mov_b32_e32 v8, v0
	v_mov_b32_e32 v9, v0
	v_mov_b32_e32 v10, v0
	v_mov_b32_e32 v11, v0
	v_mov_b32_e32 v12, v0
	v_mov_b32_e32 v13, v0
	v_mov_b32_e32 v14, v0
	v_mov_b32_e32 v15, v0
	v_mov_b32_e32 v16, v0
	v_mov_b32_e32 v17, v0
	v_mov_b32_e32 v18, v0
	v_mov_b32_e32 v19, v0
	v_mov_b32_e32 v20, v0
	v_mov_b32_e32 v21, v0
	v_mov_b32_e32 v22, v0
	v_mov_b32_e32 v23, v0
	v_mov_b32_e32 v24, v0
	v_mov_b32_e32 v25, v0
	v_mov_b32_e32 v26, v0
	v_mov_b32_e32 v27, v0
	v_mov_b32_e32 v28, v0
	v_mov_b32_e32 v29, v0
	v_mov_b32_e32 v30, v0
	v_mov_b32_e32 v31, v0
	v_mov_b32_e32 v32, v0
	v_mov_b32_e32 v33, v0
	v_mov_b32_e32 v34, v0
	v_mov_b32_e32 v35, v0
	v_mov_b32_e32 v36, v0
	v_mov_b32_e32 v37, v0
	v_mov_b32_e32 v38, v0
	v_mov_b32_e32 v39, v0
	v_mov_b32_e32 v40, v0
	v_mov_b32_e32 v41, v0
	v_mov_b32_e32 v42, v0
	v_mov_b32_e32 v43, v0
	v_mov_b32_e32 v44, v0
	v_mov_b32_e32 v45, v0
	v_mov_b32_e32 v46, v0
	v_mov_b32_e32 v47, v0
	v_mov_b32_e32 v48, v0
	v_mov_b32_e32 v49, v0
	v_mov_b32_e32 v50, v0
	v_mov_b32_e32 v51, v0
	v_mov_b32_e32 v52, v0
	v_mov_b32_e32 v53, v0
	v_mov_b32_e32 v54, v0
	v_mov_b32_e32 v55, v0
	v_mov_b32_e32 v56, v0
	v_mov_b32_e32 v57, v0
	v_mov_b32_e32 v58, v0
	v_mov_b32_e32 v59, v0
	v_mov_b32_e32 v60, v0
	v_mov_b32_e32 v61, v0
	v_mov_b32_e32 v62, v0
	v_mov_b32_e32 v63, v0
	s_barrier
	s_mul_i32 s8, s74, 0x440
	v_add_u32_e32 v242, s8, v64
	v_lshl_add_u32 v242, v242, 1, v204
	v_ashrrev_i32_e32 v243, 31, v242
	v_readlane_b32 s8, v253, 13
	v_readlane_b32 s9, v253, 14
	s_mul_i32 s36, s96, 0x22000
	s_mul_hi_u32 s37, s96, 0x22000
	s_nop 1
	s_add_u32 s8, s8, s36
	s_addc_u32 s9, s9, s37
	s_add_u32 s8, s8, 0x400000
	s_addc_u32 s9, s9, 0
	v_lshl_add_u64 v[242:243], v[242:243], 2, s[8:9]
	global_load_dwordx2 v[240:241], v[242:243], off

; #define LAS __attribute__((address_space(3)))
;     __device__ __forceinline__ void fused(const Acc& acc, const Unit& u, int wr, int wc, int fr, int fq, LAS unsigned char* lds, int wid, int lane) const {
;         LAS float* Es = (LAS float*)lds;
; #pragma unroll
;         for (int ai = 0; ai < 2; ++ai)
; #pragma unroll
;             for (int m = 0; m < 4; ++m)
; #pragma unroll
;                 for (int n = 0; n < 2; ++n) { const int r = ai * 128 + wr * 64 + m * 16 + fr, c = wc * 32 + n * 16 + fq * 4; *(LAS f32x4*)(Es + r * 128 + c) = acc[ai][0][m][n]; }
;         __syncthreads();
;         if (wid == 0) {
;             const int g = u.z, b = u.pm, p = lane;
;             const float ar = apow[((g * 17 + 16) * 64 + p) * 2], aim = apow[((g * 17 + 16) * 64 + p) * 2 + 1];
;             float hr = 0.f, hi = 0.f;
;             bf16_t* zp = ZUT + ((size_t)g * NCHUNK + (size_t)b * 256) * KY + 256 + p;
;             float er = Es[p], ei = Es[64 + p];
.LBB0_921:
	s_lshl_b32 s0, s28, 7
	s_add_i32 s0, s0, 0
	s_lshl_b32 s1, s20, 15
	v_and_b32_e32 v66, -16, v64
	v_lshlrev_b32_e32 v65, 9, v65
	s_add_i32 s1, s1, s0
	v_add3_u32 v65, s1, v66, v65
	s_barrier
	ds_write_b128 v65, v[60:63]
	ds_write_b128 v65, v[56:59] offset:64
	ds_write_b128 v65, v[52:55] offset:8192
	ds_write_b128 v65, v[48:51] offset:8256
	ds_write_b128 v65, v[44:47] offset:16384
	ds_write_b128 v65, v[40:43] offset:16448
	ds_write_b128 v65, v[36:39] offset:24576
	ds_write_b128 v65, v[32:35] offset:24640
	v_add_u32_e32 v32, 0x10000, v65
	ds_write_b128 v32, v[28:31]
	ds_write_b128 v32, v[24:27] offset:64
	v_add_u32_e32 v24, 0x12000, v65
	ds_write_b128 v24, v[20:23]
	ds_write_b128 v24, v[16:19] offset:64
	v_add_u32_e32 v16, 0x14000, v65
	ds_write_b128 v16, v[12:15]
	ds_write_b128 v16, v[8:11] offset:64
	v_add_u32_e32 v8, 0x16000, v65
	s_cmp_lg_u32 s19, 0
	s_movk_i32 s24, 0x7e
	ds_write_b128 v8, v[4:7]
	ds_write_b128 v8, v[0:3] offset:64
	s_waitcnt vmcnt(0) lgkmcnt(0)
	s_barrier
	s_cbranch_scc1 .LBB0_925
	s_mul_i32 s2, s74, 0x440
	s_mul_i32 s0, s96, 0x22000
	v_readlane_b32 s6, v253, 13
	v_add_u32_e32 v0, s2, v64
	s_mul_hi_u32 s1, s96, 0x22000
	v_readlane_b32 s7, v253, 14
	s_add_u32 s0, s6, s0
	v_lshl_add_u32 v0, v0, 1, v204
	s_addc_u32 s1, s7, s1
	v_ashrrev_i32_e32 v1, 31, v0
	v_lshl_add_u64 v[0:1], v[0:1], 2, s[0:1]
	s_mov_b32 s0, 0x400000
	v_add_co_u32_e32 v0, vcc, s0, v0
	s_add_u32 s1, s17, s18
	s_nop 0
	v_addc_co_u32_e32 v1, vcc, 0, v1, vcc
	v_mov_b32_e32 v0, v240
	v_mov_b32_e32 v1, v241
	s_addc_u32 s5, s16, 0
	s_add_u32 s4, s6, s1
	v_ashrrev_i32_e32 v65, 31, v64
	s_addc_u32 s5, s7, s5
	v_mov_b32_e32 v6, 0
	s_mov_b64 s[2:3], 0x11d00880
	v_lshl_add_u64 v[2:3], v[64:65], 1, s[4:5]
	s_mov_b32 s0, 0
	v_lshl_add_u32 v8, v64, 2, 0
	v_lshl_add_u64 v[2:3], v[2:3], 0, s[2:3]
	v_mov_b32_e32 v7, v6
	s_waitcnt vmcnt(0)
	v_pk_mov_b32 v[4:5], v[0:1], v[0:1] op_sel:[1,0]

; __device__ __forceinline__ void attn_prompt_unit(unsigned char* lds, const bf16_t* Q, const bf16_t* Kb, const bf16_t* Vb, bf16_t* MIX, const float* sinks, int unit, int tid) {
;     ...
;     const int wid = tid >> 6, lane = tid & 63;
;     __syncthreads();
; #pragma unroll
;     for (int i = 0; i < 4; ++i) { const int ch = tid + 512 * i, kj = ch >> 3, c8 = ch & 7; const int tok = nb * 128 - 128 + kj;
;         u32x4 kv = (u32x4){0u, 0u, 0u, 0u}, vv = kv;
;         if (tok >= 0) { const size_t off = ((size_t)b * SEQ + tok) * 128 + kvh * 64 + c8 * 8; kv = *(const u32x4*)(Kb + off); vv = *(const u32x4*)(Vb + off); }
.LBB0_928:
	s_bfe_u32 s8, s15, 0x50001
	s_ashr_i32 s0, s15, 6
	s_and_b32 s9, s15, 1
	s_lshl_b32 s10, s8, 7
	s_ashr_i32 s1, s0, 31
	s_add_i32 s11, s10, 0xffffff80
	s_lshl_b64 s[6:7], s[0:1], 19
	s_lshl_b32 s16, s9, 6
	s_or_b32 s6, s6, s16
	v_mov_b32_e32 v15, s7
	v_or_b32_e32 v14, s6, v114
	s_barrier
	v_add_u32_e32 v160, s11, v131
	v_cmp_lt_i32_e32 vcc, -1, v160
	v_mov_b32_e32 v16, 0
	v_mov_b32_e32 v17, 0
	v_mov_b32_e32 v18, 0
	v_mov_b32_e32 v19, 0
	v_mov_b32_e32 v20, 0
	v_mov_b32_e32 v21, 0
	v_mov_b32_e32 v22, 0
	v_mov_b32_e32 v23, 0
	s_and_saveexec_b64 s[6:7], vcc
	s_cbranch_execz .Lmy_pst_0
	v_lshlrev_b64 v[2:3], 7, v[160:161]
	v_lshl_add_u64 v[2:3], v[2:3], 0, v[14:15]
	v_lshlrev_b64 v[2:3], 1, v[2:3]
	v_lshl_add_u64 v[6:7], s[4:5], 0, v[2:3]
	v_lshl_add_u64 v[2:3], s[2:3], 0, v[2:3]
	global_load_dwordx4 v[16:19], v[2:3], off
	global_load_dwordx4 v[20:23], v[6:7], off
